# v65 plus phase 8: the 32 sample spatial-gate items handed to workgroups 128..159 (sample-memory workgroups) instead of 0..31 (prompt-memory workgroups)
# baseline (speedup 1.0000x reference)
.LBB0_1290:
	s_add_i32 s77, s77, s46
	s_add_i32 s76, s76, s46
	s_add_i32 s69, s69, s46
	s_cmpk_lg_u32 s46, 0x100
	s_cbranch_scc1 .Lp8_noremap
	s_cmpk_lt_i32 s77, 0x300
	s_cbranch_scc1 .Lp8_noremap
	s_cmpk_ge_i32 s77, 0x400
	s_cbranch_scc1 .Lp8_noremap
	s_sub_i32 s2, s77, 0x300
	s_add_i32 s3, s2, 0x80
	s_and_b32 s3, s3, 0xff
	s_sub_i32 s3, s3, s2
	s_add_i32 s77, s77, s3
	s_add_i32 s76, s76, s3
	s_add_i32 s69, s69, s3
.Lp8_noremap:
	s_cmpk_gt_i32 s77, 0x31f
	s_cbranch_scc1 .LBB0_1331
